# metafuse + wtlate A/C: late weight-transposition items at P2 start on even workgroups, after the SSM items on odd workgroups
# speedup vs baseline: 1.0027x; 1.0027x over previous
; __device__ __forceinline__ void p0_prologue(const Args& a, LAS unsigned char* lds, int wave, int lane) {
;     ...
;     for (int it = gw; it < NITEMS; it += NGW) {
;         int r = it;
;         if (r < I1) { transpose_item(a.in[3], INC, a.in[2], DM, NQKVU, (bf16*)(ws + WS_W1), false, scr, r, lane); continue; } r -= I1;
;         if (r < IG) { transpose_item(a.in[3] + NQKVU, INC, a.in[2], DM, 2048, (bf16*)(ws + WS_WG), true, scr, r, lane); continue; } r -= IG;
;         if (r < I2) { transpose_item(a.in[15], 2048, nullptr, DM, 2048, (bf16*)(ws + WS_W2), true, scr, r, lane); continue; } r -= I2;
;         if (r < I3) { transpose_item(a.in[18], DM, nullptr, DM, DM, (bf16*)(ws + WS_W3), false, scr, r, lane); continue; } r -= I3;
;         if (r < I4) { transpose_item(a.in[20], 2 * DFF, a.in[19], DM, 2 * DFF, (bf16*)(ws + WS_W4), true, scr, r, lane, true); continue; } r -= I4;
;         transpose_item(a.in[21], DM, nullptr, DFF, DM, (bf16*)(ws + WS_W5), false, scr, r, lane);
;     }
.LBB0_20:
	s_add_i32 s49, s49, s96
	s_add_i32 s14, s14, s15
	s_add_i32 s16, s16, s17
	s_add_i32 s18, s18, s19
	s_add_i32 s20, s20, s21
	s_cmpk_gt_i32 s49, 0x7bf
	s_cbranch_scc0 .LBB0_21
	s_cmp_eq_u32 s101, 1
	s_cbranch_scc1 .Lwt_ret1
	s_cmp_eq_u32 s101, 3
	s_cbranch_scc1 .Lwt_ret3
	s_branch .LBB0_88

; __device__ __forceinline__ void attn_item(const Args& a, LAS unsigned char* lds, int item, int wave, int lane) {
;     ...
;     const int r = wave >> 1, qh = wave & 1, hq = kvh * 4 + r, ql = lane & 31, hi = lane >> 5;
;     const float sink = a.in[6][hq];
;     const float* qnw = a.in[4];
;     const float L2E = 1.4426950408889634f;
;     for (int q4 = 0; q4 < 4; ++q4) {
;         const int bl = q4 >> 1, qb = q4 & 1, blk = blk0 + bl;
;         const int qblk = 2 * qh + qb;
;         const size_t qrow = (size_t)b * SEQ + blk * 128 + qblk * 32 + ql;
;         bf16x8 qf[4];
;         {
;             u32x4 qw[4]; float ss = 0.f;
; #pragma unroll
;             for (int ks = 0; ks < 4; ++ks) { qw[ks] = *(const u32x4*)(QB + qrow * DM + hq * 64 + 16 * ks + 8 * hi);
;                 const unsigned ww[4] = {qw[ks].x, qw[ks].y, qw[ks].z, qw[ks].w};
; #pragma unroll
;                 for (int e = 0; e < 4; ++e) { const float lo = bf_lo(ww[e]), h2 = bf_hi(ww[e]); ss += lo * lo + h2 * h2; } }
;             ss += __shfl_xor(ss, 32);
;             const float rs = __builtin_amdgcn_rsqf(ss * (1.0f / 64.0f) + EPS) * 0.125f;
; #pragma unroll
;             for (int ks = 0; ks < 4; ++ks) { const f32x4 g0 = *(const f32x4*)(qnw + 16 * ks + 8 * hi), g1 = *(const f32x4*)(qnw + 16 * ks + 8 * hi + 4);
;                 u32x4 o; o.x = cvt_pk(bf_lo(qw[ks].x) * rs * g0.x, bf_hi(qw[ks].x) * rs * g0.y); o.y = cvt_pk(bf_lo(qw[ks].y) * rs * g0.z, bf_hi(qw[ks].y) * rs * g0.w);
;                 o.z = cvt_pk(bf_lo(qw[ks].z) * rs * g1.x, bf_hi(qw[ks].z) * rs * g1.y); o.w = cvt_pk(bf_lo(qw[ks].w) * rs * g1.z, bf_hi(qw[ks].w) * rs * g1.w);
;                 qf[ks] = __builtin_bit_cast(bf16x8, o); }
;         }
;         f32x16 S[6];
; #pragma unroll
;         for (int i = 0; i < 6; ++i) {
;             const int kb = (i == 0) ? 0 : 4 * bl + qblk + i;
;             f32x16 acc;
; #pragma unroll
;             for (int e = 0; e < 16; ++e) acc[e] = 0.f;
; #pragma unroll
;             for (int ks = 0; ks < 4; ++ks) { const bf16x8 kf = *(const LAS bf16x8*)(lds + ATT_K_OFF + (kb * 32 + ql) * KP + (16 * ks + 8 * hi) * 2);
;                 acc = __builtin_amdgcn_mfma_f32_32x32x16_bf16(kf, qf[ks], acc, 0, 0, 0); }
;             S[i] = acc;
;         }
;         const float NEG = -INFINITY;
; #pragma unroll
;         for (int e = 0; e < 16; ++e) { const int kr = crow(e, hi);
.LBB0_245:
	s_or_b64 exec, exec, s[0:1]
	s_add_u32 s60, s58, 0x60000
	s_addc_u32 s61, s59, 0
	s_cmpk_lt_i32 s2, 0x200
	s_cselect_b64 s[54:55], -1, 0
	s_cmpk_gt_i32 s2, 0x1ff
	v_lshrrev_b32_e32 v105, 5, v128
	v_cmp_gt_u32_e64 s[0:1], 32, v128
	v_or_b32_e32 v104, 32, v128
	s_waitcnt lgkmcnt(0)
	s_barrier
	s_bitcmp0_b32 s2, 0
	s_cbranch_scc0 .Lwt_skip3
	v_mov_b32_e32 v169, v104
	v_mov_b32_e32 v170, v105
	v_mov_b32_e32 v171, v116
	v_mov_b32_e32 v172, s48
	v_mov_b32_e32 v173, s49
	v_mov_b32_e32 v174, s50
	v_mov_b32_e32 v175, s51
	v_mov_b32_e32 v176, s52
	v_mov_b32_e32 v177, s53
	v_mov_b32_e32 v178, s54
	v_mov_b32_e32 v179, s55
	v_mov_b32_e32 v180, s0
	v_mov_b32_e32 v181, s1
	v_mov_b32_e32 v182, s4
	v_mov_b32_e32 v183, s5
	v_mov_b32_e32 v184, s6
	v_mov_b32_e32 v185, s7
	v_mov_b32_e32 v0, 0x23f80
	ds_read_b64 v[0:1], v0
	s_waitcnt lgkmcnt(0)
	v_readfirstlane_b32 s4, v0
	v_readfirstlane_b32 s5, v1
	s_load_dwordx8 s[48:55], s[4:5], 0x90
	s_load_dwordx2 s[74:75], s[4:5], 0x78
	s_load_dwordx4 s[80:83], s[4:5], 0x10
	s_add_i32 s38, s33, s40
	s_addk_i32 s38, 0x7c0
	v_lshlrev_b32_e32 v112, 4, v224
	v_and_b32_e32 v131, 7, v224
	s_mov_b32 s101, 3
	s_waitcnt lgkmcnt(0)
	s_branch .Lwt_setup
.Lwt_ret3:
	v_mov_b32_e32 v104, v169
	v_mov_b32_e32 v105, v170
	v_mov_b32_e32 v116, v171
	v_readfirstlane_b32 s48, v172
	v_readfirstlane_b32 s49, v173
	v_readfirstlane_b32 s50, v174
	v_readfirstlane_b32 s51, v175
	v_readfirstlane_b32 s52, v176
	v_readfirstlane_b32 s53, v177
	v_readfirstlane_b32 s54, v178
	v_readfirstlane_b32 s55, v179
	v_readfirstlane_b32 s0, v180
	v_readfirstlane_b32 s1, v181
	v_readfirstlane_b32 s4, v182
	v_readfirstlane_b32 s5, v183
	v_readfirstlane_b32 s6, v184
	v_readfirstlane_b32 s7, v185
	s_waitcnt lgkmcnt(0)
	s_barrier
.Lwt_skip3:
	s_cmpk_gt_i32 s2, 0x1ff
	s_cbranch_scc1 .LBB0_261
	v_mbcnt_hi_u32_b32 v2, -1, v235
	v_and_b32_e32 v1, 64, v2
	v_xor_b32_e32 v0, 1, v2
	v_add_u32_e32 v3, 64, v1
	v_cmp_lt_i32_e32 vcc, v0, v3
	v_mov_b32_e32 v99, 0
	v_mov_b32_e32 v1, v99
	v_cndmask_b32_e32 v0, v2, v0, vcc
	v_lshlrev_b32_e32 v113, 2, v0
	v_xor_b32_e32 v0, 2, v2
	v_cmp_lt_i32_e32 vcc, v0, v3
	v_lshlrev_b32_e32 v96, 4, v131
	v_mov_b32_e32 v97, v99
	v_cndmask_b32_e32 v0, v2, v0, vcc
	v_lshlrev_b32_e32 v124, 2, v0
	v_xor_b32_e32 v0, 4, v2
	v_cmp_lt_i32_e32 vcc, v0, v3
	v_lshlrev_b32_e32 v98, 5, v131
	v_lshl_add_u64 v[100:101], s[4:5], 0, v[96:97]
	v_cndmask_b32_e32 v0, v2, v0, vcc
	v_lshlrev_b32_e32 v125, 2, v0
	v_lshlrev_b32_e32 v0, 4, v105
	v_lshl_add_u64 v[108:109], s[48:49], 0, v[0:1]
	v_xor_b32_e32 v1, 32, v2
	v_cmp_lt_i32_e32 vcc, v1, v3
	v_lshl_add_u64 v[106:107], s[86:87], 0, v[98:99]
	s_lshl_b32 s4, s33, 1
	v_lshlrev_b32_e32 v98, 3, v105
	v_cndmask_b32_e32 v1, v2, v1, vcc
	v_and_b32_e32 v2, 32, v128
	v_mov_b32_e32 v3, v99
	v_lshl_add_u64 v[102:103], s[6:7], 0, v[96:97]
	s_and_b32 s65, s4, 2
	v_lshlrev_b32_e32 v97, 2, v1
	v_lshl_add_u64 v[110:111], s[84:85], 0, v[2:3]
	v_add_u32_e32 v112, 0, v0
	v_lshlrev_b32_e32 v2, 2, v105
	v_lshl_add_u64 v[0:1], s[58:59], 0, v[98:99]
	s_mov_b64 s[4:5], 0x19400000
	v_lshl_add_u64 v[114:115], v[0:1], 0, s[4:5]
	v_or_b32_e32 v1, 2, v2
	v_cmp_gt_u32_e64 s[8:9], v1, v130
	v_or_b32_e32 v1, 3, v2
	v_cmp_gt_u32_e64 s[10:11], v1, v130
	v_or_b32_e32 v1, 8, v2
	v_cmp_gt_u32_e64 s[12:13], v1, v130
	v_or_b32_e32 v1, 9, v2
	v_cmp_gt_u32_e64 s[14:15], v1, v130
	v_or_b32_e32 v1, 10, v2
	v_cmp_gt_u32_e64 s[16:17], v1, v130
	v_or_b32_e32 v1, 11, v2
	v_cmp_gt_u32_e64 s[18:19], v1, v130
	v_or_b32_e32 v1, 16, v2
	v_cmp_gt_u32_e64 s[20:21], v1, v130
	v_or_b32_e32 v1, 17, v2
	v_cmp_gt_u32_e64 s[22:23], v1, v130
	v_or_b32_e32 v1, 18, v2
	v_cmp_gt_u32_e64 s[24:25], v1, v130
	v_or_b32_e32 v1, 19, v2
	v_cmp_gt_u32_e64 s[26:27], v1, v130
	v_or_b32_e32 v1, 24, v2
	v_cmp_gt_u32_e64 s[28:29], v1, v130
	v_or_b32_e32 v1, 25, v2
	v_cmp_gt_u32_e64 s[30:31], v1, v130
	v_or_b32_e32 v1, 26, v2
	s_lshr_b32 s41, s41, 7
	v_cmp_gt_u32_e64 s[34:35], v1, v130
	v_or_b32_e32 v1, 27, v2
	v_mul_u32_u24_e32 v4, 0x1a30, v131
	v_sub_u32_e32 v3, v112, v98
	s_movk_i32 s76, 0x90
	v_mul_u32_u24_e32 v0, 0x90, v130
	v_cmp_gt_u32_e64 s[36:37], v1, v130
	s_cmp_eq_u32 s65, 0
	s_movk_i32 s42, 0x348
	v_lshlrev_b32_e32 v1, 1, v141
	s_mov_b32 s63, 0
	v_cmp_gt_u32_e64 s[4:5], v2, v130
	v_cmp_lt_u32_e64 s[6:7], v2, v130
	s_cselect_b64 s[38:39], -1, 0
	v_mad_u32_u24 v126, v130, s42, v3
	v_mad_u32_u24 v127, v104, s42, v3
	v_or_b32_e32 v132, 0x8000, v141
	v_add3_u32 v133, v4, v1, 0
	v_mad_u32_u24 v134, v141, s76, 0
	s_lshl_b32 s77, s2, 1
	s_lshl_b32 s78, s92, 1
	s_movk_i32 s79, 0x7f
	s_movk_i32 s80, 0x100
	s_movk_i32 s81, 0x500
	v_mov_b32_e32 v135, 0x358637bd
	s_movk_i32 s82, 0xaff
	s_mov_b32 s64, 0x3fb8aa3b
	v_add_u32_e32 v136, v112, v0
	s_mov_b32 s83, 0xff800000
	v_mov_b32_e32 v137, 0xff800000
	s_mov_b32 s84, s2
	s_branch .LBB0_248

; __global__ void __launch_bounds__(NTHREADS, 2) mk_fwd(Args a) {
;     ...
;     for (int it = c; it < 256 + 8; it += G) ssm_item<false>(a, lds, it, wave, lane);
;     xcd_barrier(bar);
;     for (int it = c; it < 256; it += G) ssm_item<true>(a, lds, it, wave, lane);
.LBB0_274:
	s_bitcmp1_b32 s2, 0
	s_cbranch_scc0 .Lwt_skip1
	s_barrier
	v_mov_b32_e32 v169, v104
	v_mov_b32_e32 v170, v105
	v_mov_b32_e32 v171, v116
	v_mov_b32_e32 v172, s48
	v_mov_b32_e32 v173, s49
	v_mov_b32_e32 v174, s50
	v_mov_b32_e32 v175, s51
	v_mov_b32_e32 v176, s52
	v_mov_b32_e32 v177, s53
	v_mov_b32_e32 v178, s54
	v_mov_b32_e32 v179, s55
	v_mov_b32_e32 v0, 0x23f80
	ds_read_b64 v[0:1], v0
	s_waitcnt lgkmcnt(0)
	v_readfirstlane_b32 s4, v0
	v_readfirstlane_b32 s5, v1
	s_load_dwordx8 s[48:55], s[4:5], 0x90
	s_load_dwordx2 s[74:75], s[4:5], 0x78
	s_load_dwordx4 s[80:83], s[4:5], 0x10
	s_add_i32 s38, s33, s40
	s_addk_i32 s38, 0x7c0
	v_lshlrev_b32_e32 v112, 4, v224
	v_and_b32_e32 v131, 7, v224
	s_mov_b32 s101, 1
	s_waitcnt lgkmcnt(0)
	s_branch .Lwt_setup
.Lwt_ret1:
	v_mov_b32_e32 v104, v169
	v_mov_b32_e32 v105, v170
	v_mov_b32_e32 v116, v171
	v_readfirstlane_b32 s48, v172
	v_readfirstlane_b32 s49, v173
	v_readfirstlane_b32 s50, v174
	v_readfirstlane_b32 s51, v175
	v_readfirstlane_b32 s52, v176
	v_readfirstlane_b32 s53, v177
	v_readfirstlane_b32 s54, v178
	v_readfirstlane_b32 s55, v179
